# v94 plus M3 item: epilogue gate/om loads issued in two batches, K-loop decay loads issued together
# baseline (speedup 1.0000x reference)
.LBB0_1035:
	v_mad_i64_i32 v[66:67], s[40:41], v142, s83, v[132:133]
	v_add_u32_e32 v70, 8, v142
	global_load_dwordx4 v[66:69], v[66:67], off offset:1024
	v_mad_i64_i32 v[70:71], s[40:41], v70, s83, v[132:133]
	v_add_u32_e32 v74, 16, v142
	global_load_dwordx4 v[70:73], v[70:71], off offset:1024
	v_mad_i64_i32 v[74:75], s[40:41], v74, s83, v[132:133]
	v_add_u32_e32 v78, 24, v142
	global_load_dwordx4 v[74:77], v[74:75], off offset:1024
	v_mad_i64_i32 v[78:79], s[40:41], v78, s83, v[132:133]
	global_load_dwordx4 v[78:81], v[78:79], off offset:1024
	s_cmp_lt_u32 s61, s95
	s_cselect_b64 s[74:75], -1, 0
	s_or_b64 s[40:41], s[74:75], vcc
	s_add_i32 s61, s61, 1
	v_add_u32_e32 v142, 32, v142
	s_waitcnt vmcnt(3)
	ds_write_b128 v144, v[66:69]
	s_waitcnt vmcnt(2)
	ds_write_b128 v144, v[70:73] offset:1152
	s_waitcnt vmcnt(1)
	ds_write_b128 v144, v[74:77] offset:2304
	s_waitcnt vmcnt(0)
	ds_write_b128 v144, v[78:81] offset:3456
	s_waitcnt lgkmcnt(0)
	ds_read_b128 v[66:69], v145
	ds_read_b128 v[148:151], v145 offset:32
	s_waitcnt lgkmcnt(1)
	v_mfma_f32_32x32x16_bf16 v[66:81], v[66:69], v[96:99], 0
	s_waitcnt lgkmcnt(0)
	v_mfma_f32_32x32x16_bf16 v[66:81], v[148:151], v[104:107], v[66:81]
	ds_read_b128 v[148:151], v145 offset:64
	s_waitcnt lgkmcnt(0)
	v_mfma_f32_32x32x16_bf16 v[66:81], v[148:151], v[108:111], v[66:81]
	ds_read_b128 v[148:151], v145 offset:96
	s_waitcnt lgkmcnt(0)
	v_mfma_f32_32x32x16_bf16 v[66:81], v[148:151], v[112:115], v[66:81]
	global_load_dwordx4 v[212:215], v[136:137], off offset:-96
	global_load_dwordx4 v[216:219], v[136:137], off offset:-64
	global_load_dwordx4 v[220:223], v[136:137], off offset:-32
	global_load_dwordx4 v[236:239], v[136:137], off
	s_waitcnt vmcnt(0)
	s_nop 1
	v_mov_b64_e32 v[148:149], v[212:213]
	v_mov_b64_e32 v[150:151], v[214:215]
	s_nop 0
	v_sub_f32_e32 v82, v148, v140
	v_mul_f32_e32 v82, 0x3fb8aa3b, v82
	v_exp_f32_e32 v82, v82
	s_nop 6
	v_mul_f32_e32 v66, v66, v82
	v_cndmask_b32_e64 v82, 0, v66, s[40:41]
	v_add_f32_e32 v66, v146, v82
	v_sub_f32_e32 v146, v149, v140
	v_mul_f32_e32 v146, 0x3fb8aa3b, v146
	v_exp_f32_e32 v146, v146
	s_or_b64 s[40:41], s[74:75], s[8:9]
	v_mul_f32_e32 v67, v67, v146
	v_cndmask_b32_e64 v146, 0, v67, s[40:41]
	v_sub_f32_e32 v67, v150, v140
	v_mul_f32_e32 v67, 0x3fb8aa3b, v67
	v_exp_f32_e32 v67, v67
	s_or_b64 s[40:41], s[74:75], s[10:11]
	v_add_f32_e32 v66, v146, v66
	v_mul_f32_e32 v67, v68, v67
	v_cndmask_b32_e64 v147, 0, v67, s[40:41]
	v_sub_f32_e32 v67, v151, v140
	v_mul_f32_e32 v67, 0x3fb8aa3b, v67
	v_exp_f32_e32 v67, v67
	s_or_b64 s[40:41], s[74:75], s[12:13]
	v_add_f32_e32 v66, v147, v66
	v_mul_f32_e32 v67, v69, v67
	v_cndmask_b32_e64 v148, 0, v67, s[40:41]
	v_add_f32_e32 v149, v148, v66
	s_nop 1
	v_mov_b64_e32 v[66:67], v[216:217]
	v_mov_b64_e32 v[68:69], v[218:219]
	s_or_b64 s[40:41], s[74:75], s[14:15]
	s_nop 0
	v_sub_f32_e32 v66, v66, v140
	v_mul_f32_e32 v66, 0x3fb8aa3b, v66
	v_sub_f32_e32 v67, v67, v140
	v_exp_f32_e32 v66, v66
	v_mul_f32_e32 v67, 0x3fb8aa3b, v67
	v_exp_f32_e32 v67, v67
	v_mul_f32_e32 v66, v70, v66
	v_cndmask_b32_e64 v70, 0, v66, s[40:41]
	s_or_b64 s[40:41], s[74:75], s[16:17]
	v_mul_f32_e32 v67, v71, v67
	v_cndmask_b32_e64 v71, 0, v67, s[40:41]
	v_sub_f32_e32 v67, v68, v140
	v_mul_f32_e32 v67, 0x3fb8aa3b, v67
	v_exp_f32_e32 v67, v67
	s_or_b64 s[40:41], s[74:75], s[18:19]
	v_add_f32_e32 v66, v70, v149
	v_add_f32_e32 v66, v71, v66
	v_mul_f32_e32 v67, v72, v67
	v_cndmask_b32_e64 v72, 0, v67, s[40:41]
	v_sub_f32_e32 v67, v69, v140
	v_mul_f32_e32 v67, 0x3fb8aa3b, v67
	v_exp_f32_e32 v67, v67
	s_or_b64 s[40:41], s[74:75], s[20:21]
	v_add_f32_e32 v66, v72, v66
	v_mul_f32_e32 v67, v73, v67
	v_cndmask_b32_e64 v73, 0, v67, s[40:41]
	v_add_f32_e32 v149, v73, v66
	s_nop 1
	v_mov_b64_e32 v[66:67], v[220:221]
	v_mov_b64_e32 v[68:69], v[222:223]
	s_or_b64 s[40:41], s[74:75], s[22:23]
	s_nop 0
	v_sub_f32_e32 v66, v66, v140
	v_mul_f32_e32 v66, 0x3fb8aa3b, v66
	v_sub_f32_e32 v67, v67, v140
	v_exp_f32_e32 v66, v66
	v_mul_f32_e32 v67, 0x3fb8aa3b, v67
	v_exp_f32_e32 v67, v67
	v_mul_f32_e32 v66, v74, v66
	v_cndmask_b32_e64 v74, 0, v66, s[40:41]
	s_or_b64 s[40:41], s[74:75], s[24:25]
	v_mul_f32_e32 v67, v75, v67
	v_cndmask_b32_e64 v75, 0, v67, s[40:41]
	v_sub_f32_e32 v67, v68, v140
	v_mul_f32_e32 v67, 0x3fb8aa3b, v67
	v_exp_f32_e32 v67, v67
	s_or_b64 s[40:41], s[74:75], s[26:27]
	v_add_f32_e32 v66, v74, v149
	v_add_f32_e32 v66, v75, v66
	v_mul_f32_e32 v67, v76, v67
	v_cndmask_b32_e64 v76, 0, v67, s[40:41]
	v_sub_f32_e32 v67, v69, v140
	v_mul_f32_e32 v67, 0x3fb8aa3b, v67
	v_exp_f32_e32 v67, v67
	s_or_b64 s[40:41], s[74:75], s[28:29]
	v_add_f32_e32 v66, v76, v66
	v_mul_f32_e32 v67, v77, v67
	v_cndmask_b32_e64 v77, 0, v67, s[40:41]
	v_add_f32_e32 v149, v77, v66
	s_nop 1
	v_mov_b64_e32 v[66:67], v[236:237]
	v_mov_b64_e32 v[68:69], v[238:239]
	s_or_b64 s[40:41], s[74:75], s[30:31]
	v_lshl_add_u64 v[136:137], v[136:137], 0, s[68:69]
	s_nop 0
	v_sub_f32_e32 v66, v66, v140
	v_mul_f32_e32 v66, 0x3fb8aa3b, v66
	v_sub_f32_e32 v67, v67, v140
	v_exp_f32_e32 v66, v66
	v_mul_f32_e32 v67, 0x3fb8aa3b, v67
	v_exp_f32_e32 v67, v67
	v_mul_f32_e32 v66, v78, v66
	v_cndmask_b32_e64 v150, 0, v66, s[40:41]
	s_or_b64 s[40:41], s[74:75], s[34:35]
	v_mul_f32_e32 v67, v79, v67
	v_add_f32_e32 v66, v150, v149
	v_cndmask_b32_e64 v149, 0, v67, s[40:41]
	v_sub_f32_e32 v67, v68, v140
	v_mul_f32_e32 v67, 0x3fb8aa3b, v67
	v_exp_f32_e32 v67, v67
	s_or_b64 s[40:41], s[74:75], s[36:37]
	v_add_f32_e32 v66, v149, v66
	s_nop 0
	v_mul_f32_e32 v67, v80, v67
	v_cndmask_b32_e64 v80, 0, v67, s[40:41]
	v_add_f32_e32 v78, v80, v66
	v_sub_f32_e32 v66, v69, v140
	v_mul_f32_e32 v66, 0x3fb8aa3b, v66
	v_exp_f32_e32 v66, v66
	s_or_b64 s[40:41], s[74:75], s[38:39]
	s_nop 0
	s_nop 0
	v_mul_f32_e32 v66, v81, v66
	v_cndmask_b32_e64 v79, 0, v66, s[40:41]
	s_nop 0
	s_nop 0
	s_nop 0
	v_cvt_pk_bf16_f32 v66, v82, v146
	s_nop 0
	s_nop 0
	s_nop 0
	s_nop 0
	v_cvt_pk_bf16_f32 v67, v147, v148
	s_nop 0
	s_nop 0
	s_nop 0
	s_nop 0
	s_nop 0
	v_cvt_pk_bf16_f32 v68, v70, v71
	v_cvt_pk_bf16_f32 v69, v72, v73
	v_cvt_pk_bf16_f32 v70, v74, v75
	v_cvt_pk_bf16_f32 v71, v76, v77
	v_cvt_pk_bf16_f32 v72, v150, v149
	v_bfe_u32 v73, v80, 16, 1
	v_add3_u32 v73, v80, v73, s73
	v_bfe_u32 v74, v79, 16, 1
	v_lshrrev_b32_e32 v73, 16, v73
	v_add3_u32 v74, v79, v74, s73
	v_add_u32_e32 v80, s60, v1
	v_and_or_b32 v73, v74, s33, v73
	v_add_u32_e32 v81, 0x880, v80
	ds_read_b64_tr_b16 v[74:75], v80
	ds_read_b64_tr_b16 v[76:77], v81
	s_waitcnt lgkmcnt(0)
	v_add_u32_e32 v81, 0x1100, v80
	v_mfma_f32_32x32x16_bf16 v[2:17], v[74:77], v[66:69], v[2:17]
	v_add_u32_e32 v82, 0x1980, v80
	ds_read_b64_tr_b16 v[74:75], v81
	ds_read_b64_tr_b16 v[76:77], v82
	s_waitcnt lgkmcnt(0)
	v_add_u32_e32 v81, 64, v80
	v_add_u32_e32 v82, 0x8c0, v80
	s_addk_i32 s60, 0x2200
	v_add_f32_e32 v146, v79, v78
	s_cmp_lg_u32 s66, s60
	v_mfma_f32_32x32x16_bf16 v[2:17], v[74:77], v[70:73], v[2:17]
	ds_read_b64_tr_b16 v[74:75], v81
	ds_read_b64_tr_b16 v[76:77], v82
	s_waitcnt lgkmcnt(0)
	v_add_u32_e32 v81, 0x1140, v80
	v_add_u32_e32 v82, 0x19c0, v80
	v_mfma_f32_32x32x16_bf16 v[18:33], v[74:77], v[66:69], v[18:33]
	ds_read_b64_tr_b16 v[74:75], v81
	ds_read_b64_tr_b16 v[76:77], v82
	s_waitcnt lgkmcnt(0)
	v_add_u32_e32 v81, 0x80, v80
	v_add_u32_e32 v82, 0x900, v80
	v_mfma_f32_32x32x16_bf16 v[18:33], v[74:77], v[70:73], v[18:33]
	ds_read_b64_tr_b16 v[74:75], v81
	ds_read_b64_tr_b16 v[76:77], v82
	s_waitcnt lgkmcnt(0)
	v_add_u32_e32 v81, 0x1180, v80
	v_add_u32_e32 v82, 0x1a00, v80
	v_mfma_f32_32x32x16_bf16 v[34:49], v[74:77], v[66:69], v[34:49]
	ds_read_b64_tr_b16 v[74:75], v81
	ds_read_b64_tr_b16 v[76:77], v82
	s_waitcnt lgkmcnt(0)
	v_add_u32_e32 v81, 0xc0, v80
	v_add_u32_e32 v82, 0x940, v80
	v_mfma_f32_32x32x16_bf16 v[34:49], v[74:77], v[70:73], v[34:49]
	ds_read_b64_tr_b16 v[74:75], v81
	ds_read_b64_tr_b16 v[76:77], v82
	s_waitcnt lgkmcnt(0)
	s_nop 0
	v_mfma_f32_32x32x16_bf16 v[50:65], v[74:77], v[66:69], v[50:65]
	v_add_u32_e32 v74, 0x11c0, v80
	v_add_u32_e32 v75, 0x1a40, v80
	ds_read_b64_tr_b16 v[66:67], v74
	ds_read_b64_tr_b16 v[68:69], v75
	s_waitcnt lgkmcnt(0)
	s_nop 0
	v_mfma_f32_32x32x16_bf16 v[50:65], v[66:69], v[70:73], v[50:65]
	s_cbranch_scc1 .LBB0_1035
	v_readlane_b32 s8, v254, 53
	v_readlane_b32 s9, v254, 54
	s_lshl_b64 s[8:9], s[8:9], 2
	s_add_u32 s10, s64, s8
	v_or_b32_e32 v82, s55, v141
	v_mov_b64_e32 v[66:67], s[62:63]
	s_addc_u32 s11, s65, s9
	v_mad_u64_u32 v[66:67], s[8:9], v82, s83, v[66:67]
	s_lshl_b32 s70, s54, 1
	v_lshl_add_u64 v[66:67], v[66:67], 0, s[70:71]
	v_lshl_add_u64 v[96:97], v[134:135], 1, v[66:67]
	v_add_co_u32_e32 v66, vcc, s82, v96
	s_mov_b64 s[8:9], 0x1000
	s_nop 0
	v_addc_co_u32_e32 v67, vcc, 0, v97, vcc
	global_load_dwordx2 v[104:105], v[66:67], off
	v_mfma_f32_32x32x16_bf16 v[66:81], v[128:131], v[88:91], 0
	v_lshl_add_u64 v[88:89], v[96:97], 0, s[8:9]
	global_load_dwordx2 v[98:99], v[88:89], off offset:16
	v_xor_b32_e32 v1, 32, v249
	s_lshl_b32 s8, s54, 2
	s_add_u32 s8, s10, s8
	s_addc_u32 s9, s11, 0
	v_lshlrev_b32_e32 v96, 3, v143
	v_mfma_f32_32x32x16_bf16 v[66:81], v[124:127], v[84:87], v[66:81]
	v_and_b32_e32 v84, 64, v249
	v_add_u32_e32 v86, 64, v84
	v_cmp_lt_i32_e32 vcc, v1, v86
	v_add_f32_e32 v85, v139, v140
	v_or_b32_e32 v87, v84, v138
	v_cndmask_b32_e32 v1, v249, v1, vcc
	v_lshlrev_b32_e32 v1, 2, v1
	v_mfma_f32_32x32x16_bf16 v[66:81], v[120:123], v[92:95], v[66:81]
	v_mul_f32_e32 v90, 0xbfb8aa3b, v85
	v_lshlrev_b64 v[84:85], 12, v[82:83]
	v_lshlrev_b32_e32 v82, 2, v87
	ds_bpermute_b32 v87, v1, v146
	v_exp_f32_e32 v86, v90
	v_lshl_add_u64 v[84:85], s[88:89], 0, v[84:85]
	v_lshl_add_u64 v[94:95], v[84:85], 0, s[70:71]
	v_mfma_f32_32x32x16_bf16 v[66:81], v[116:119], v[100:103], v[66:81]
	s_mov_b32 s62, 0x1b81e000
	s_nop 10
	ds_bpermute_b32 v66, v82, v66
	s_waitcnt lgkmcnt(1)
	v_add_f32_e32 v67, v146, v87
	v_lshl_add_u64 v[74:75], v[134:135], 2, s[8:9]
	s_mov_b32 s8, 0xf800000
	s_waitcnt lgkmcnt(0)
	v_add_f32_e32 v66, v67, v66
	v_max_f32_e64 v66, |v66|, v86
	v_div_scale_f32 v67, s[10:11], v66, v66, 1.0
	v_rcp_f32_e32 v68, v67
	v_div_scale_f32 v69, vcc, 1.0, v66, 1.0
	v_fma_f32 v70, -v67, v68, 1.0
	v_fmac_f32_e32 v68, v70, v68
	v_mul_f32_e32 v70, v69, v68
	v_fma_f32 v71, -v67, v70, v69
	v_fmac_f32_e32 v70, v71, v68
	v_fma_f32 v67, -v67, v70, v69
	v_div_fmas_f32 v67, v67, v68, v70
	v_div_fixup_f32 v82, v67, v66, 1.0
	v_pk_mul_f32 v[68:69], v[64:65], v[82:83] op_sel_hi:[1,0]
	v_pk_mul_f32 v[126:127], v[2:3], v[82:83] op_sel_hi:[1,0]
	v_pk_mul_f32 v[102:103], v[4:5], v[82:83] op_sel_hi:[1,0]
	v_pk_mul_f32 v[128:129], v[126:127], v[126:127]
	v_pk_mul_f32 v[72:73], v[60:61], v[82:83] op_sel_hi:[1,0]
	v_pk_mul_f32 v[70:71], v[62:63], v[82:83] op_sel_hi:[1,0]
	v_pk_mul_f32 v[118:119], v[102:103], v[102:103]
	v_pk_mul_f32 v[122:123], v[8:9], v[82:83] op_sel_hi:[1,0]
	v_pk_mul_f32 v[130:131], v[6:7], v[82:83] op_sel_hi:[1,0]
	v_pk_mul_f32 v[110:111], v[12:13], v[82:83] op_sel_hi:[1,0]
	v_pk_mul_f32 v[100:101], v[16:17], v[82:83] op_sel_hi:[1,0]
	v_pk_mul_f32 v[116:117], v[10:11], v[82:83] op_sel_hi:[1,0]
	v_pk_mul_f32 v[108:109], v[14:15], v[82:83] op_sel_hi:[1,0]
	v_pk_mul_f32 v[90:91], v[20:21], v[82:83] op_sel_hi:[1,0]
	v_pk_mul_f32 v[84:85], v[24:25], v[82:83] op_sel_hi:[1,0]
	v_pk_mul_f32 v[92:93], v[18:19], v[82:83] op_sel_hi:[1,0]
	v_pk_mul_f32 v[86:87], v[22:23], v[82:83] op_sel_hi:[1,0]
	v_pk_mul_f32 v[78:79], v[28:29], v[82:83] op_sel_hi:[1,0]
	v_pk_mul_f32 v[32:33], v[32:33], v[82:83] op_sel_hi:[1,0]
	v_pk_mul_f32 v[80:81], v[26:27], v[82:83] op_sel_hi:[1,0]
	v_pk_mul_f32 v[28:29], v[36:37], v[82:83] op_sel_hi:[1,0]
	v_pk_mul_f32 v[24:25], v[40:41], v[82:83] op_sel_hi:[1,0]
	v_pk_mul_f32 v[26:27], v[38:39], v[82:83] op_sel_hi:[1,0]
	v_pk_mul_f32 v[20:21], v[44:45], v[82:83] op_sel_hi:[1,0]
	s_waitcnt vmcnt(0)
	v_lshlrev_b32_e32 v64, 16, v98
	v_and_b32_e32 v65, 0xffff0000, v98
	v_mul_f32_e32 v64, 0xbfb8aa3b, v64
	v_mul_f32_e32 v65, 0xbfb8aa3b, v65
	v_exp_f32_e32 v76, v64
	v_exp_f32_e32 v77, v65
	v_pk_mul_f32 v[16:17], v[48:49], v[82:83] op_sel_hi:[1,0]
	v_pk_mul_f32 v[22:23], v[42:43], v[82:83] op_sel_hi:[1,0]
	v_add_f32_e32 v76, 1.0, v76
	v_rcp_f32_e32 v120, v76
	v_add_f32_e32 v76, 1.0, v77
	v_rcp_f32_e32 v121, v76
	v_lshlrev_b32_e32 v76, 16, v99
	v_mul_f32_e32 v97, 0xbfb8aa3b, v76
	v_pk_mul_f32 v[76:77], v[30:31], v[82:83] op_sel_hi:[1,0]
	v_pk_mul_f32 v[30:31], v[34:35], v[82:83] op_sel_hi:[1,0]
	v_pk_mul_f32 v[18:19], v[46:47], v[82:83] op_sel_hi:[1,0]
	v_pk_mul_f32 v[12:13], v[52:53], v[82:83] op_sel_hi:[1,0]
	v_pk_mul_f32 v[6:7], v[56:57], v[82:83] op_sel_hi:[1,0]
	v_pk_mul_f32 v[14:15], v[50:51], v[82:83] op_sel_hi:[1,0]
	v_pk_mul_f32 v[8:9], v[54:55], v[82:83] op_sel_hi:[1,0]
	v_pk_mul_f32 v[2:3], v[58:59], v[82:83] op_sel_hi:[1,0]
	v_add_f32_e32 v82, v128, v129
	v_add_f32_e32 v82, v118, v82
	v_pk_mul_f32 v[132:133], v[130:131], v[130:131]
	v_add_f32_e32 v82, v119, v82
	v_add_f32_e32 v82, v132, v82
	v_pk_mul_f32 v[124:125], v[122:123], v[122:123]
	v_add_f32_e32 v82, v133, v82
	v_add_f32_e32 v82, v124, v82
	v_pk_mul_f32 v[10:11], v[116:117], v[116:117]
	v_add_f32_e32 v82, v125, v82
	v_add_f32_e32 v10, v10, v82
	v_pk_mul_f32 v[134:135], v[110:111], v[110:111]
	v_add_f32_e32 v10, v11, v10
	v_add_f32_e32 v10, v134, v10
	v_pk_mul_f32 v[138:139], v[108:109], v[108:109]
	v_add_f32_e32 v10, v135, v10
	v_add_f32_e32 v10, v138, v10
	v_pk_mul_f32 v[136:137], v[100:101], v[100:101]
	v_add_f32_e32 v10, v139, v10
	v_lshlrev_b32_e32 v60, 16, v104
	v_and_b32_e32 v61, 0xffff0000, v104
	v_lshlrev_b32_e32 v62, 16, v105
	v_and_b32_e32 v63, 0xffff0000, v105
	v_add_f32_e32 v10, v136, v10
	v_mul_f32_e32 v60, 0xbfb8aa3b, v60
	v_mul_f32_e32 v61, 0xbfb8aa3b, v61
	v_mul_f32_e32 v62, 0xbfb8aa3b, v62
	v_mul_f32_e32 v63, 0xbfb8aa3b, v63
	v_pk_mul_f32 v[144:145], v[92:93], v[92:93]
	v_add_f32_e32 v10, v137, v10
	v_exp_f32_e32 v60, v60
	v_exp_f32_e32 v61, v61
	v_exp_f32_e32 v62, v62
	v_exp_f32_e32 v63, v63
	v_add_f32_e32 v10, v144, v10
	v_pk_mul_f32 v[140:141], v[90:91], v[90:91]
	v_add_f32_e32 v10, v145, v10
	v_add_f32_e32 v10, v140, v10
	v_pk_mul_f32 v[146:147], v[86:87], v[86:87]
	v_add_f32_e32 v10, v141, v10
	v_add_f32_e32 v60, 1.0, v60
	v_add_f32_e32 v61, 1.0, v61
	v_add_f32_e32 v62, 1.0, v62
	v_add_f32_e32 v63, 1.0, v63
	v_add_f32_e32 v10, v146, v10
	v_rcp_f32_e32 v106, v60
	v_rcp_f32_e32 v107, v61
	v_rcp_f32_e32 v104, v62
	v_rcp_f32_e32 v105, v63
	global_load_dwordx4 v[180:183], v[74:75], off
	global_load_dwordx4 v[184:187], v[74:75], off offset:32
	global_load_dwordx2 v[188:189], v[88:89], off offset:32
	global_load_dwordx4 v[190:193], v[74:75], off offset:64
	global_load_dwordx2 v[194:195], v[88:89], off offset:48
	global_load_dwordx4 v[196:199], v[74:75], off offset:96
	global_load_dwordx2 v[200:201], v[88:89], off offset:64
	global_load_dwordx4 v[202:205], v[74:75], off offset:128
	global_load_dwordx2 v[206:207], v[88:89], off offset:80
	global_load_dwordx4 v[208:211], v[74:75], off offset:160
	global_load_dwordx2 v[212:213], v[88:89], off offset:96
	global_load_dwordx4 v[214:217], v[74:75], off offset:192
	global_load_dwordx2 v[218:219], v[88:89], off offset:112
	global_load_dwordx4 v[220:223], v[74:75], off offset:224
	s_waitcnt vmcnt(0)
	s_nop 1
	v_mov_b64_e32 v[64:65], v[180:181]
	v_mov_b64_e32 v[66:67], v[182:183]
	s_nop 1
	v_mov_b64_e32 v[60:61], v[184:185]
	v_mov_b64_e32 v[62:63], v[186:187]
	v_pk_mul_f32 v[142:143], v[84:85], v[84:85]
	v_add_f32_e32 v10, v147, v10
	v_add_f32_e32 v10, v142, v10
	v_pk_mul_f32 v[152:153], v[80:81], v[80:81]
	v_add_f32_e32 v10, v143, v10
	v_add_f32_e32 v10, v152, v10
	v_pk_mul_f32 v[148:149], v[78:79], v[78:79]
	v_add_f32_e32 v10, v153, v10
	v_add_f32_e32 v10, v148, v10
	v_pk_mul_f32 v[154:155], v[76:77], v[76:77]
	v_add_f32_e32 v10, v149, v10
	v_add_f32_e32 v10, v154, v10
	v_pk_mul_f32 v[150:151], v[32:33], v[32:33]
	v_add_f32_e32 v10, v155, v10
	v_add_f32_e32 v10, v150, v10
	v_pk_mul_f32 v[34:35], v[30:31], v[30:31]
	v_add_f32_e32 v10, v151, v10
	v_add_f32_e32 v10, v34, v10
	v_pk_mul_f32 v[36:37], v[28:29], v[28:29]
	v_add_f32_e32 v10, v35, v10
	v_add_f32_e32 v10, v36, v10
	v_pk_mul_f32 v[38:39], v[26:27], v[26:27]
	v_add_f32_e32 v10, v37, v10
	v_add_f32_e32 v10, v38, v10
	v_pk_mul_f32 v[40:41], v[24:25], v[24:25]
	v_add_f32_e32 v10, v39, v10
	v_add_f32_e32 v10, v40, v10
	v_pk_mul_f32 v[42:43], v[22:23], v[22:23]
	v_add_f32_e32 v10, v41, v10
	v_add_f32_e32 v10, v42, v10
	v_pk_mul_f32 v[44:45], v[20:21], v[20:21]
	v_add_f32_e32 v10, v43, v10
	v_add_f32_e32 v10, v44, v10
	v_pk_mul_f32 v[46:47], v[18:19], v[18:19]
	v_add_f32_e32 v10, v45, v10
	v_add_f32_e32 v10, v46, v10
	v_pk_mul_f32 v[48:49], v[16:17], v[16:17]
	v_add_f32_e32 v10, v47, v10
	v_add_f32_e32 v10, v48, v10
	v_pk_mul_f32 v[50:51], v[14:15], v[14:15]
	v_add_f32_e32 v10, v49, v10
	v_add_f32_e32 v10, v50, v10
	v_pk_mul_f32 v[52:53], v[12:13], v[12:13]
	v_add_f32_e32 v10, v51, v10
	v_add_f32_e32 v10, v52, v10
	v_pk_mul_f32 v[54:55], v[8:9], v[8:9]
	v_add_f32_e32 v10, v53, v10
	v_add_f32_e32 v10, v54, v10
	v_pk_mul_f32 v[56:57], v[6:7], v[6:7]
	v_add_f32_e32 v10, v55, v10
	v_add_f32_e32 v10, v56, v10
	v_pk_mul_f32 v[58:59], v[2:3], v[2:3]
	v_add_f32_e32 v10, v57, v10
	v_add_f32_e32 v10, v58, v10
	v_pk_mul_f32 v[114:115], v[72:73], v[72:73]
	v_add_f32_e32 v10, v59, v10
	v_add_f32_e32 v10, v114, v10
	v_pk_mul_f32 v[112:113], v[70:71], v[70:71]
	v_add_f32_e32 v10, v115, v10
	v_add_f32_e32 v10, v112, v10
	v_pk_mul_f32 v[4:5], v[68:69], v[68:69]
	v_add_f32_e32 v10, v113, v10
	v_add_f32_e32 v4, v4, v10
	v_add_f32_e32 v4, v5, v4
	ds_bpermute_b32 v1, v1, v4
	v_and_b32_e32 v10, 0xffff0000, v99
	v_exp_f32_e32 v5, v97
	v_mul_f32_e32 v10, 0xbfb8aa3b, v10
	v_exp_f32_e32 v11, v10
	s_waitcnt lgkmcnt(0)
	v_add_f32_e32 v1, v4, v1
	v_fmamk_f32 v1, v1, 0x3c000000, v245
	v_mul_f32_e32 v4, 0x4f800000, v1
	v_cmp_gt_f32_e32 vcc, s8, v1
	v_add_f32_e32 v5, 1.0, v5
	v_rcp_f32_e32 v10, v5
	v_cndmask_b32_e32 v1, v1, v4, vcc
	v_sqrt_f32_e32 v4, v1
	v_add_f32_e32 v5, 1.0, v11
	v_ashrrev_i32_e32 v97, 31, v96
	v_lshl_add_u64 v[42:43], v[96:97], 1, v[94:95]
	v_add_u32_e32 v11, -1, v4
	v_fma_f32 v34, -v11, v4, v1
	v_cmp_ge_f32_e64 s[8:9], 0, v34
	v_add_u32_e32 v34, 1, v4
	s_nop 0
	v_cndmask_b32_e64 v11, v4, v11, s[8:9]
	v_fma_f32 v4, -v34, v4, v1
	v_cmp_lt_f32_e64 s[8:9], 0, v4
	s_nop 1
	v_cndmask_b32_e64 v4, v11, v34, s[8:9]
	v_mul_f32_e32 v11, 0x37800000, v4
	v_cndmask_b32_e32 v4, v4, v11, vcc
	v_cmp_class_f32_e32 vcc, v1, v251
	v_rcp_f32_e32 v11, v5
	s_nop 0
	v_cndmask_b32_e32 v1, v4, v1, vcc
	v_div_scale_f32 v4, s[8:9], v1, v1, 1.0
	v_rcp_f32_e32 v34, v4
	s_mov_b64 s[8:9], 0x1b81e000
	v_fma_f32 v5, -v4, v34, 1.0
	v_fmac_f32_e32 v34, v5, v34
	v_div_scale_f32 v5, vcc, 1.0, v1, 1.0
	v_mul_f32_e32 v35, v5, v34
	v_fma_f32 v36, -v4, v35, v5
	v_fmac_f32_e32 v35, v36, v34
	v_fma_f32 v4, -v4, v35, v5
	v_div_fmas_f32 v4, v4, v34, v35
	v_div_fixup_f32 v4, v4, v1, 1.0
	v_pk_mul_f32 v[34:35], v[126:127], v[4:5] op_sel_hi:[1,0]
	v_pk_mul_f32 v[36:37], v[102:103], v[4:5] op_sel_hi:[1,0]
	s_nop 0
	v_pk_mul_f32 v[34:35], v[64:65], v[34:35]
	v_pk_mul_f32 v[36:37], v[66:67], v[36:37]
	v_pk_mul_f32 v[34:35], v[106:107], v[34:35]
	v_pk_mul_f32 v[36:37], v[104:105], v[36:37]
	v_and_b32_sdwa v5, v34, v247 dst_sel:DWORD dst_unused:UNUSED_PAD src0_sel:WORD_1 src1_sel:DWORD
	v_and_b32_sdwa v1, v35, v247 dst_sel:DWORD dst_unused:UNUSED_PAD src0_sel:WORD_1 src1_sel:DWORD
	v_add3_u32 v5, v34, v5, s73
	v_add3_u32 v1, v35, v1, s73
	v_lshrrev_b32_e32 v5, 16, v5
	v_and_or_b32 v34, v1, s33, v5
	v_and_b32_sdwa v5, v36, v247 dst_sel:DWORD dst_unused:UNUSED_PAD src0_sel:WORD_1 src1_sel:DWORD
	v_add3_u32 v5, v36, v5, s73
	v_and_b32_sdwa v1, v37, v247 dst_sel:DWORD dst_unused:UNUSED_PAD src0_sel:WORD_1 src1_sel:DWORD
	v_lshrrev_b32_e32 v5, 16, v5
	v_add3_u32 v1, v37, v1, s73
	v_pk_mul_f32 v[36:37], v[130:131], v[4:5] op_sel_hi:[1,0]
	v_and_or_b32 v35, v1, s33, v5
	s_nop 0
	v_pk_mul_f32 v[36:37], v[60:61], v[36:37]
	v_pk_mul_f32 v[38:39], v[122:123], v[4:5] op_sel_hi:[1,0]
	v_pk_mul_f32 v[36:37], v[120:121], v[36:37]
	v_pk_mul_f32 v[38:39], v[62:63], v[38:39]
	v_and_b32_sdwa v5, v36, v247 dst_sel:DWORD dst_unused:UNUSED_PAD src0_sel:WORD_1 src1_sel:DWORD
	v_and_b32_sdwa v1, v37, v247 dst_sel:DWORD dst_unused:UNUSED_PAD src0_sel:WORD_1 src1_sel:DWORD
	v_add3_u32 v5, v36, v5, s73
	v_pk_mul_f32 v[10:11], v[10:11], v[38:39]
	v_add3_u32 v1, v37, v1, s73
	v_lshrrev_b32_e32 v5, 16, v5
	v_and_or_b32 v36, v1, s33, v5
	v_and_b32_sdwa v5, v10, v247 dst_sel:DWORD dst_unused:UNUSED_PAD src0_sel:WORD_1 src1_sel:DWORD
	v_and_b32_sdwa v1, v11, v247 dst_sel:DWORD dst_unused:UNUSED_PAD src0_sel:WORD_1 src1_sel:DWORD
	v_add3_u32 v5, v10, v5, s73
	v_add3_u32 v1, v11, v1, s73
	v_lshrrev_b32_e32 v5, 16, v5
	v_and_or_b32 v37, v1, s33, v5
	v_add_co_u32_e32 v10, vcc, s62, v42
	v_permlane32_swap_b32_e32 v34, v36
	v_permlane32_swap_b32_e32 v35, v37
	v_addc_co_u32_e32 v11, vcc, 0, v43, vcc
	global_store_dwordx4 v[10:11], v[34:37], off
	s_nop 1
	v_mov_b64_e32 v[44:45], v[188:189]
	s_nop 0
	s_nop 1
	v_mov_b64_e32 v[34:35], v[190:191]
	v_mov_b64_e32 v[36:37], v[192:193]
	s_nop 1
	v_mov_b64_e32 v[46:47], v[194:195]
	s_nop 1
	v_mov_b64_e32 v[38:39], v[196:197]
	v_mov_b64_e32 v[40:41], v[198:199]
	v_lshl_add_u64 v[10:11], v[42:43], 0, s[8:9]
	s_mov_b64 s[8:9], 0
	s_nop 0
	v_lshlrev_b32_e32 v1, 16, v44
	v_mul_f32_e32 v1, 0xbfb8aa3b, v1
	v_and_b32_e32 v5, 0xffff0000, v44
	v_exp_f32_e32 v1, v1
	v_mul_f32_e32 v5, 0xbfb8aa3b, v5
	v_exp_f32_e32 v5, v5
	v_and_b32_e32 v43, 0xffff0000, v45
	v_add_f32_e32 v1, 1.0, v1
	v_rcp_f32_e32 v42, v1
	v_pk_mul_f32 v[48:49], v[116:117], v[4:5] op_sel_hi:[1,0]
	v_add_f32_e32 v1, 1.0, v5
	v_lshlrev_b32_e32 v5, 16, v45
	v_mul_f32_e32 v5, 0xbfb8aa3b, v5
	v_exp_f32_e32 v5, v5
	v_mul_f32_e32 v43, 0xbfb8aa3b, v43
	v_exp_f32_e32 v45, v43
	v_rcp_f32_e32 v43, v1
	v_add_f32_e32 v1, 1.0, v5
	v_rcp_f32_e32 v44, v1
	v_add_f32_e32 v1, 1.0, v45
	s_nop 0
	v_pk_mul_f32 v[34:35], v[34:35], v[48:49]
	v_rcp_f32_e32 v45, v1
	v_pk_mul_f32 v[34:35], v[42:43], v[34:35]
	v_pk_mul_f32 v[42:43], v[110:111], v[4:5] op_sel_hi:[1,0]
	v_and_b32_sdwa v5, v34, v247 dst_sel:DWORD dst_unused:UNUSED_PAD src0_sel:WORD_1 src1_sel:DWORD
	v_pk_mul_f32 v[36:37], v[36:37], v[42:43]
	v_and_b32_sdwa v1, v35, v247 dst_sel:DWORD dst_unused:UNUSED_PAD src0_sel:WORD_1 src1_sel:DWORD
	v_add3_u32 v5, v34, v5, s73
	v_pk_mul_f32 v[36:37], v[44:45], v[36:37]
	v_add3_u32 v1, v35, v1, s73
	v_lshrrev_b32_e32 v5, 16, v5
	v_and_or_b32 v34, v1, s33, v5
	v_and_b32_sdwa v5, v36, v247 dst_sel:DWORD dst_unused:UNUSED_PAD src0_sel:WORD_1 src1_sel:DWORD
	v_and_b32_sdwa v1, v37, v247 dst_sel:DWORD dst_unused:UNUSED_PAD src0_sel:WORD_1 src1_sel:DWORD
	s_nop 0
	v_lshlrev_b32_e32 v35, 16, v46
	v_add3_u32 v5, v36, v5, s73
	v_add3_u32 v1, v37, v1, s73
	v_mul_f32_e32 v35, 0xbfb8aa3b, v35
	v_lshrrev_b32_e32 v5, 16, v5
	v_exp_f32_e32 v37, v35
	v_and_or_b32 v35, v1, s33, v5
	v_and_b32_e32 v5, 0xffff0000, v46
	v_mul_f32_e32 v5, 0xbfb8aa3b, v5
	v_exp_f32_e32 v5, v5
	v_add_f32_e32 v1, 1.0, v37
	v_rcp_f32_e32 v36, v1
	v_and_b32_e32 v37, 0xffff0000, v47
	v_pk_mul_f32 v[42:43], v[108:109], v[4:5] op_sel_hi:[1,0]
	v_add_f32_e32 v1, 1.0, v5
	v_lshlrev_b32_e32 v5, 16, v47
	v_mul_f32_e32 v5, 0xbfb8aa3b, v5
	v_exp_f32_e32 v5, v5
	v_mul_f32_e32 v37, 0xbfb8aa3b, v37
	s_nop 0
	v_pk_mul_f32 v[38:39], v[38:39], v[42:43]
	v_exp_f32_e32 v43, v37
	v_rcp_f32_e32 v37, v1
	v_add_f32_e32 v1, 1.0, v5
	v_rcp_f32_e32 v42, v1
	v_add_f32_e32 v1, 1.0, v43
	v_rcp_f32_e32 v43, v1
	v_pk_mul_f32 v[36:37], v[36:37], v[38:39]
	v_pk_mul_f32 v[38:39], v[100:101], v[4:5] op_sel_hi:[1,0]
	v_and_b32_sdwa v5, v36, v247 dst_sel:DWORD dst_unused:UNUSED_PAD src0_sel:WORD_1 src1_sel:DWORD
	v_pk_mul_f32 v[38:39], v[40:41], v[38:39]
	v_and_b32_sdwa v1, v37, v247 dst_sel:DWORD dst_unused:UNUSED_PAD src0_sel:WORD_1 src1_sel:DWORD
	v_add3_u32 v5, v36, v5, s73
	v_pk_mul_f32 v[38:39], v[42:43], v[38:39]
	v_add3_u32 v1, v37, v1, s73
	v_lshrrev_b32_e32 v5, 16, v5
	v_and_or_b32 v36, v1, s33, v5
	v_and_b32_sdwa v5, v38, v247 dst_sel:DWORD dst_unused:UNUSED_PAD src0_sel:WORD_1 src1_sel:DWORD
	v_and_b32_sdwa v1, v39, v247 dst_sel:DWORD dst_unused:UNUSED_PAD src0_sel:WORD_1 src1_sel:DWORD
	v_add3_u32 v5, v38, v5, s73
	v_add3_u32 v1, v39, v1, s73
	v_lshrrev_b32_e32 v5, 16, v5
	v_and_or_b32 v37, v1, s33, v5
	v_permlane32_swap_b32_e32 v34, v36
	s_nop 0
	v_permlane32_swap_b32_e32 v35, v37
	global_store_dwordx4 v[10:11], v[34:37], off offset:32
	s_nop 1
	v_mov_b64_e32 v[42:43], v[200:201]
	s_nop 0
	s_nop 1
	v_mov_b64_e32 v[34:35], v[202:203]
	v_mov_b64_e32 v[36:37], v[204:205]
	s_nop 1
	v_mov_b64_e32 v[44:45], v[206:207]
	s_nop 1
	v_mov_b64_e32 v[38:39], v[208:209]
	v_mov_b64_e32 v[40:41], v[210:211]
	s_nop 0
	v_lshlrev_b32_e32 v1, 16, v42
	v_mul_f32_e32 v1, 0xbfb8aa3b, v1
	v_and_b32_e32 v5, 0xffff0000, v42
	v_exp_f32_e32 v1, v1
	v_mul_f32_e32 v5, 0xbfb8aa3b, v5
	v_exp_f32_e32 v5, v5
	v_add_f32_e32 v1, 1.0, v1
	v_rcp_f32_e32 v42, v1
	v_pk_mul_f32 v[46:47], v[92:93], v[4:5] op_sel_hi:[1,0]
	v_add_f32_e32 v1, 1.0, v5
	v_lshlrev_b32_e32 v5, 16, v43
	v_mul_f32_e32 v5, 0xbfb8aa3b, v5
	v_and_b32_e32 v43, 0xffff0000, v43
	v_exp_f32_e32 v5, v5
	v_mul_f32_e32 v43, 0xbfb8aa3b, v43
	s_nop 0
	v_pk_mul_f32 v[34:35], v[34:35], v[46:47]
	v_exp_f32_e32 v47, v43
	v_rcp_f32_e32 v43, v1
	v_add_f32_e32 v1, 1.0, v5
	v_rcp_f32_e32 v46, v1
	v_add_f32_e32 v1, 1.0, v47
	v_rcp_f32_e32 v47, v1
	v_pk_mul_f32 v[34:35], v[42:43], v[34:35]
	v_pk_mul_f32 v[42:43], v[90:91], v[4:5] op_sel_hi:[1,0]
	v_and_b32_sdwa v5, v34, v247 dst_sel:DWORD dst_unused:UNUSED_PAD src0_sel:WORD_1 src1_sel:DWORD
	v_pk_mul_f32 v[36:37], v[36:37], v[42:43]
	v_and_b32_sdwa v1, v35, v247 dst_sel:DWORD dst_unused:UNUSED_PAD src0_sel:WORD_1 src1_sel:DWORD
	v_add3_u32 v5, v34, v5, s73
	v_pk_mul_f32 v[36:37], v[46:47], v[36:37]
	v_add3_u32 v1, v35, v1, s73
	v_lshrrev_b32_e32 v5, 16, v5
	v_and_or_b32 v34, v1, s33, v5
	v_and_b32_sdwa v5, v36, v247 dst_sel:DWORD dst_unused:UNUSED_PAD src0_sel:WORD_1 src1_sel:DWORD
	v_and_b32_sdwa v1, v37, v247 dst_sel:DWORD dst_unused:UNUSED_PAD src0_sel:WORD_1 src1_sel:DWORD
	s_nop 0
	v_lshlrev_b32_e32 v35, 16, v44
	v_add3_u32 v5, v36, v5, s73
	v_add3_u32 v1, v37, v1, s73
	v_mul_f32_e32 v35, 0xbfb8aa3b, v35
	v_lshrrev_b32_e32 v5, 16, v5
	v_exp_f32_e32 v37, v35
	v_and_or_b32 v35, v1, s33, v5
	v_and_b32_e32 v5, 0xffff0000, v44
	v_mul_f32_e32 v5, 0xbfb8aa3b, v5
	v_exp_f32_e32 v5, v5
	v_add_f32_e32 v1, 1.0, v37
	v_rcp_f32_e32 v36, v1
	v_and_b32_e32 v37, 0xffff0000, v45
	v_pk_mul_f32 v[42:43], v[86:87], v[4:5] op_sel_hi:[1,0]
	v_add_f32_e32 v1, 1.0, v5
	v_lshlrev_b32_e32 v5, 16, v45
	v_mul_f32_e32 v5, 0xbfb8aa3b, v5
	v_exp_f32_e32 v5, v5
	v_mul_f32_e32 v37, 0xbfb8aa3b, v37
	s_nop 0
	v_pk_mul_f32 v[38:39], v[38:39], v[42:43]
	v_exp_f32_e32 v43, v37
	v_rcp_f32_e32 v37, v1
	v_add_f32_e32 v1, 1.0, v5
	v_rcp_f32_e32 v42, v1
	v_add_f32_e32 v1, 1.0, v43
	v_rcp_f32_e32 v43, v1
	v_pk_mul_f32 v[36:37], v[36:37], v[38:39]
	v_pk_mul_f32 v[38:39], v[84:85], v[4:5] op_sel_hi:[1,0]
	v_and_b32_sdwa v5, v36, v247 dst_sel:DWORD dst_unused:UNUSED_PAD src0_sel:WORD_1 src1_sel:DWORD
	v_pk_mul_f32 v[38:39], v[40:41], v[38:39]
	v_and_b32_sdwa v1, v37, v247 dst_sel:DWORD dst_unused:UNUSED_PAD src0_sel:WORD_1 src1_sel:DWORD
	v_add3_u32 v5, v36, v5, s73
	v_pk_mul_f32 v[38:39], v[42:43], v[38:39]
	v_add3_u32 v1, v37, v1, s73
	v_lshrrev_b32_e32 v5, 16, v5
	v_and_or_b32 v36, v1, s33, v5
	v_and_b32_sdwa v5, v38, v247 dst_sel:DWORD dst_unused:UNUSED_PAD src0_sel:WORD_1 src1_sel:DWORD
	v_and_b32_sdwa v1, v39, v247 dst_sel:DWORD dst_unused:UNUSED_PAD src0_sel:WORD_1 src1_sel:DWORD
	v_add3_u32 v5, v38, v5, s73
	v_add3_u32 v1, v39, v1, s73
	v_lshrrev_b32_e32 v5, 16, v5
	v_and_or_b32 v37, v1, s33, v5
	v_permlane32_swap_b32_e32 v34, v36
	s_nop 0
	v_permlane32_swap_b32_e32 v35, v37
	global_store_dwordx4 v[10:11], v[34:37], off offset:64
	s_nop 1
	v_mov_b64_e32 v[42:43], v[212:213]
	s_nop 0
	s_nop 1
	v_mov_b64_e32 v[34:35], v[214:215]
	v_mov_b64_e32 v[36:37], v[216:217]
	s_nop 1
	v_mov_b64_e32 v[44:45], v[218:219]
	s_nop 1
	v_mov_b64_e32 v[38:39], v[220:221]
	v_mov_b64_e32 v[40:41], v[222:223]
	s_nop 0
	v_lshlrev_b32_e32 v1, 16, v42
	v_mul_f32_e32 v1, 0xbfb8aa3b, v1
	v_and_b32_e32 v5, 0xffff0000, v42
	v_exp_f32_e32 v1, v1
	v_mul_f32_e32 v5, 0xbfb8aa3b, v5
	v_exp_f32_e32 v5, v5
	v_add_f32_e32 v1, 1.0, v1
	v_rcp_f32_e32 v42, v1
	v_pk_mul_f32 v[46:47], v[80:81], v[4:5] op_sel_hi:[1,0]
	v_add_f32_e32 v1, 1.0, v5
	v_lshlrev_b32_e32 v5, 16, v43
	v_mul_f32_e32 v5, 0xbfb8aa3b, v5
	v_and_b32_e32 v43, 0xffff0000, v43
	v_exp_f32_e32 v5, v5
	v_mul_f32_e32 v43, 0xbfb8aa3b, v43
	s_nop 0
	v_pk_mul_f32 v[34:35], v[34:35], v[46:47]
	v_exp_f32_e32 v47, v43
	v_rcp_f32_e32 v43, v1
	v_add_f32_e32 v1, 1.0, v5
	v_rcp_f32_e32 v46, v1
	v_add_f32_e32 v1, 1.0, v47
	v_rcp_f32_e32 v47, v1
	v_pk_mul_f32 v[34:35], v[42:43], v[34:35]
	v_pk_mul_f32 v[42:43], v[78:79], v[4:5] op_sel_hi:[1,0]
	v_and_b32_sdwa v5, v34, v247 dst_sel:DWORD dst_unused:UNUSED_PAD src0_sel:WORD_1 src1_sel:DWORD
	v_pk_mul_f32 v[36:37], v[36:37], v[42:43]
	v_and_b32_sdwa v1, v35, v247 dst_sel:DWORD dst_unused:UNUSED_PAD src0_sel:WORD_1 src1_sel:DWORD
	v_add3_u32 v5, v34, v5, s73
	v_pk_mul_f32 v[36:37], v[46:47], v[36:37]
	v_add3_u32 v1, v35, v1, s73
	v_lshrrev_b32_e32 v5, 16, v5
	v_and_or_b32 v34, v1, s33, v5
	v_and_b32_sdwa v5, v36, v247 dst_sel:DWORD dst_unused:UNUSED_PAD src0_sel:WORD_1 src1_sel:DWORD
	v_and_b32_sdwa v1, v37, v247 dst_sel:DWORD dst_unused:UNUSED_PAD src0_sel:WORD_1 src1_sel:DWORD
	s_nop 0
	v_lshlrev_b32_e32 v35, 16, v44
	v_add3_u32 v5, v36, v5, s73
	v_add3_u32 v1, v37, v1, s73
	v_mul_f32_e32 v35, 0xbfb8aa3b, v35
	v_lshrrev_b32_e32 v5, 16, v5
	v_exp_f32_e32 v37, v35
	v_and_or_b32 v35, v1, s33, v5
	v_and_b32_e32 v5, 0xffff0000, v44
	v_mul_f32_e32 v5, 0xbfb8aa3b, v5
	v_exp_f32_e32 v5, v5
	v_add_f32_e32 v1, 1.0, v37
	v_rcp_f32_e32 v36, v1
	v_and_b32_e32 v37, 0xffff0000, v45
	v_pk_mul_f32 v[42:43], v[76:77], v[4:5] op_sel_hi:[1,0]
	v_add_f32_e32 v1, 1.0, v5
	v_lshlrev_b32_e32 v5, 16, v45
	v_mul_f32_e32 v5, 0xbfb8aa3b, v5
	v_exp_f32_e32 v5, v5
	v_mul_f32_e32 v37, 0xbfb8aa3b, v37
	s_nop 0
	v_pk_mul_f32 v[38:39], v[38:39], v[42:43]
	v_exp_f32_e32 v43, v37
	v_rcp_f32_e32 v37, v1
	v_add_f32_e32 v1, 1.0, v5
	v_rcp_f32_e32 v42, v1
	v_add_f32_e32 v1, 1.0, v43
	v_rcp_f32_e32 v43, v1
	v_pk_mul_f32 v[36:37], v[36:37], v[38:39]
	v_pk_mul_f32 v[32:33], v[32:33], v[4:5] op_sel_hi:[1,0]
	v_and_b32_sdwa v5, v36, v247 dst_sel:DWORD dst_unused:UNUSED_PAD src0_sel:WORD_1 src1_sel:DWORD
	v_pk_mul_f32 v[32:33], v[40:41], v[32:33]
	v_and_b32_sdwa v1, v37, v247 dst_sel:DWORD dst_unused:UNUSED_PAD src0_sel:WORD_1 src1_sel:DWORD
	v_add3_u32 v5, v36, v5, s73
	v_pk_mul_f32 v[32:33], v[42:43], v[32:33]
	v_add3_u32 v1, v37, v1, s73
	v_lshrrev_b32_e32 v5, 16, v5
	v_and_or_b32 v36, v1, s33, v5
	v_and_b32_sdwa v5, v32, v247 dst_sel:DWORD dst_unused:UNUSED_PAD src0_sel:WORD_1 src1_sel:DWORD
	v_and_b32_sdwa v1, v33, v247 dst_sel:DWORD dst_unused:UNUSED_PAD src0_sel:WORD_1 src1_sel:DWORD
	v_add3_u32 v5, v32, v5, s73
	v_add3_u32 v1, v33, v1, s73
	v_lshrrev_b32_e32 v5, 16, v5
	v_and_or_b32 v37, v1, s33, v5
	v_permlane32_swap_b32_e32 v34, v36
	s_nop 0
	v_permlane32_swap_b32_e32 v35, v37
	global_store_dwordx4 v[10:11], v[34:37], off offset:96
	global_load_dwordx2 v[180:181], v[88:89], off offset:128
	global_load_dwordx4 v[182:185], v[74:75], off offset:256
	global_load_dwordx2 v[186:187], v[88:89], off offset:144
	global_load_dwordx4 v[188:191], v[74:75], off offset:288
	global_load_dwordx2 v[192:193], v[88:89], off offset:160
	global_load_dwordx4 v[194:197], v[74:75], off offset:320
	global_load_dwordx2 v[198:199], v[88:89], off offset:176
	global_load_dwordx4 v[200:203], v[74:75], off offset:352
	global_load_dwordx2 v[204:205], v[88:89], off offset:192
	global_load_dwordx4 v[206:209], v[74:75], off offset:384
	global_load_dwordx2 v[210:211], v[88:89], off offset:208
	global_load_dwordx4 v[212:215], v[74:75], off offset:416
	global_load_dwordx2 v[216:217], v[88:89], off offset:224
	global_load_dwordx4 v[218:221], v[74:75], off offset:448
	global_load_dwordx2 v[222:223], v[88:89], off offset:240
	global_load_dwordx4 v[236:239], v[74:75], off offset:480
	s_waitcnt vmcnt(0)
	s_nop 1
	v_mov_b64_e32 v[40:41], v[180:181]
	s_nop 0
	s_nop 1
	v_mov_b64_e32 v[32:33], v[182:183]
	v_mov_b64_e32 v[34:35], v[184:185]
	s_nop 1
	v_mov_b64_e32 v[42:43], v[186:187]
	s_nop 1
	v_mov_b64_e32 v[36:37], v[188:189]
	v_mov_b64_e32 v[38:39], v[190:191]
	s_nop 0
	v_lshlrev_b32_e32 v1, 16, v40
	v_mul_f32_e32 v1, 0xbfb8aa3b, v1
	v_and_b32_e32 v5, 0xffff0000, v40
	v_exp_f32_e32 v1, v1
	v_mul_f32_e32 v5, 0xbfb8aa3b, v5
	v_exp_f32_e32 v5, v5
	v_add_f32_e32 v1, 1.0, v1
	v_rcp_f32_e32 v40, v1
	v_pk_mul_f32 v[30:31], v[30:31], v[4:5] op_sel_hi:[1,0]
	v_add_f32_e32 v1, 1.0, v5
	v_lshlrev_b32_e32 v5, 16, v41
	s_nop 0
	v_pk_mul_f32 v[30:31], v[32:33], v[30:31]
	v_mul_f32_e32 v5, 0xbfb8aa3b, v5
	v_and_b32_e32 v32, 0xffff0000, v41
	v_exp_f32_e32 v5, v5
	v_mul_f32_e32 v32, 0xbfb8aa3b, v32
	v_exp_f32_e32 v33, v32
	v_rcp_f32_e32 v41, v1
	v_add_f32_e32 v1, 1.0, v5
	v_rcp_f32_e32 v32, v1
	v_add_f32_e32 v1, 1.0, v33
	v_rcp_f32_e32 v33, v1
	v_pk_mul_f32 v[30:31], v[40:41], v[30:31]
	v_pk_mul_f32 v[28:29], v[28:29], v[4:5] op_sel_hi:[1,0]
	v_and_b32_sdwa v5, v30, v247 dst_sel:DWORD dst_unused:UNUSED_PAD src0_sel:WORD_1 src1_sel:DWORD
	v_pk_mul_f32 v[28:29], v[34:35], v[28:29]
	v_and_b32_sdwa v1, v31, v247 dst_sel:DWORD dst_unused:UNUSED_PAD src0_sel:WORD_1 src1_sel:DWORD
	v_add3_u32 v5, v30, v5, s73
	v_pk_mul_f32 v[32:33], v[32:33], v[28:29]
	v_add3_u32 v1, v31, v1, s73
	v_lshrrev_b32_e32 v5, 16, v5
	v_and_or_b32 v28, v1, s33, v5
	v_and_b32_sdwa v5, v32, v247 dst_sel:DWORD dst_unused:UNUSED_PAD src0_sel:WORD_1 src1_sel:DWORD
	v_and_b32_sdwa v1, v33, v247 dst_sel:DWORD dst_unused:UNUSED_PAD src0_sel:WORD_1 src1_sel:DWORD
	s_nop 0
	v_lshlrev_b32_e32 v29, 16, v42
	v_add3_u32 v5, v32, v5, s73
	v_add3_u32 v1, v33, v1, s73
	v_mul_f32_e32 v29, 0xbfb8aa3b, v29
	v_lshrrev_b32_e32 v5, 16, v5
	v_exp_f32_e32 v30, v29
	v_and_or_b32 v29, v1, s33, v5
	v_and_b32_e32 v5, 0xffff0000, v42
	v_mul_f32_e32 v5, 0xbfb8aa3b, v5
	v_exp_f32_e32 v5, v5
	v_add_f32_e32 v1, 1.0, v30
	v_rcp_f32_e32 v30, v1
	v_and_b32_e32 v31, 0xffff0000, v43
	v_pk_mul_f32 v[26:27], v[26:27], v[4:5] op_sel_hi:[1,0]
	v_add_f32_e32 v1, 1.0, v5
	v_lshlrev_b32_e32 v5, 16, v43
	v_mul_f32_e32 v5, 0xbfb8aa3b, v5
	v_exp_f32_e32 v5, v5
	v_mul_f32_e32 v31, 0xbfb8aa3b, v31
	v_exp_f32_e32 v33, v31
	v_rcp_f32_e32 v31, v1
	v_add_f32_e32 v1, 1.0, v5
	v_rcp_f32_e32 v32, v1
	v_add_f32_e32 v1, 1.0, v33
	s_nop 0
	v_pk_mul_f32 v[26:27], v[36:37], v[26:27]
	v_rcp_f32_e32 v33, v1
	v_pk_mul_f32 v[26:27], v[30:31], v[26:27]
	v_pk_mul_f32 v[24:25], v[24:25], v[4:5] op_sel_hi:[1,0]
	v_and_b32_sdwa v5, v26, v247 dst_sel:DWORD dst_unused:UNUSED_PAD src0_sel:WORD_1 src1_sel:DWORD
	v_pk_mul_f32 v[24:25], v[38:39], v[24:25]
	v_and_b32_sdwa v1, v27, v247 dst_sel:DWORD dst_unused:UNUSED_PAD src0_sel:WORD_1 src1_sel:DWORD
	v_add3_u32 v5, v26, v5, s73
	v_pk_mul_f32 v[24:25], v[32:33], v[24:25]
	v_add3_u32 v1, v27, v1, s73
	v_lshrrev_b32_e32 v5, 16, v5
	v_and_or_b32 v30, v1, s33, v5
	v_and_b32_sdwa v5, v24, v247 dst_sel:DWORD dst_unused:UNUSED_PAD src0_sel:WORD_1 src1_sel:DWORD
	v_and_b32_sdwa v1, v25, v247 dst_sel:DWORD dst_unused:UNUSED_PAD src0_sel:WORD_1 src1_sel:DWORD
	v_add3_u32 v5, v24, v5, s73
	v_add3_u32 v1, v25, v1, s73
	v_lshrrev_b32_e32 v5, 16, v5
	v_and_or_b32 v31, v1, s33, v5
	v_permlane32_swap_b32_e32 v28, v30
	s_nop 0
	v_permlane32_swap_b32_e32 v29, v31
	global_store_dwordx4 v[10:11], v[28:31], off offset:128
	s_nop 1
	v_mov_b64_e32 v[32:33], v[192:193]
	s_nop 1
	v_mov_b64_e32 v[24:25], v[194:195]
	v_mov_b64_e32 v[26:27], v[196:197]
	s_nop 1
	v_mov_b64_e32 v[34:35], v[198:199]
	s_nop 0
	s_nop 1
	v_mov_b64_e32 v[28:29], v[200:201]
	v_mov_b64_e32 v[30:31], v[202:203]
	s_nop 0
	v_lshlrev_b32_e32 v1, 16, v32
	v_mul_f32_e32 v1, 0xbfb8aa3b, v1
	v_and_b32_e32 v5, 0xffff0000, v32
	v_exp_f32_e32 v1, v1
	v_mul_f32_e32 v5, 0xbfb8aa3b, v5
	v_exp_f32_e32 v5, v5
	v_add_f32_e32 v1, 1.0, v1
	v_rcp_f32_e32 v32, v1
	v_pk_mul_f32 v[22:23], v[22:23], v[4:5] op_sel_hi:[1,0]
	v_add_f32_e32 v1, 1.0, v5
	v_lshlrev_b32_e32 v5, 16, v33
	s_nop 0
	v_pk_mul_f32 v[22:23], v[24:25], v[22:23]
	v_mul_f32_e32 v5, 0xbfb8aa3b, v5
	v_and_b32_e32 v24, 0xffff0000, v33
	v_exp_f32_e32 v5, v5
	v_mul_f32_e32 v24, 0xbfb8aa3b, v24
	v_exp_f32_e32 v25, v24
	v_rcp_f32_e32 v33, v1
	v_add_f32_e32 v1, 1.0, v5
	v_rcp_f32_e32 v24, v1
	v_add_f32_e32 v1, 1.0, v25
	v_rcp_f32_e32 v25, v1
	v_pk_mul_f32 v[22:23], v[32:33], v[22:23]
	v_pk_mul_f32 v[20:21], v[20:21], v[4:5] op_sel_hi:[1,0]
	v_and_b32_sdwa v5, v22, v247 dst_sel:DWORD dst_unused:UNUSED_PAD src0_sel:WORD_1 src1_sel:DWORD
	v_pk_mul_f32 v[20:21], v[26:27], v[20:21]
	v_and_b32_sdwa v1, v23, v247 dst_sel:DWORD dst_unused:UNUSED_PAD src0_sel:WORD_1 src1_sel:DWORD
	v_add3_u32 v5, v22, v5, s73
	v_pk_mul_f32 v[24:25], v[24:25], v[20:21]
	v_add3_u32 v1, v23, v1, s73
	v_lshrrev_b32_e32 v5, 16, v5
	v_and_or_b32 v20, v1, s33, v5
	v_and_b32_sdwa v5, v24, v247 dst_sel:DWORD dst_unused:UNUSED_PAD src0_sel:WORD_1 src1_sel:DWORD
	v_and_b32_sdwa v1, v25, v247 dst_sel:DWORD dst_unused:UNUSED_PAD src0_sel:WORD_1 src1_sel:DWORD
	s_nop 0
	v_lshlrev_b32_e32 v21, 16, v34
	v_add3_u32 v5, v24, v5, s73
	v_add3_u32 v1, v25, v1, s73
	v_mul_f32_e32 v21, 0xbfb8aa3b, v21
	v_lshrrev_b32_e32 v5, 16, v5
	v_exp_f32_e32 v22, v21
	v_and_or_b32 v21, v1, s33, v5
	v_and_b32_e32 v5, 0xffff0000, v34
	v_mul_f32_e32 v5, 0xbfb8aa3b, v5
	v_exp_f32_e32 v5, v5
	v_add_f32_e32 v1, 1.0, v22
	v_rcp_f32_e32 v22, v1
	v_and_b32_e32 v23, 0xffff0000, v35
	v_pk_mul_f32 v[18:19], v[18:19], v[4:5] op_sel_hi:[1,0]
	v_add_f32_e32 v1, 1.0, v5
	v_lshlrev_b32_e32 v5, 16, v35
	v_mul_f32_e32 v5, 0xbfb8aa3b, v5
	v_exp_f32_e32 v5, v5
	v_mul_f32_e32 v23, 0xbfb8aa3b, v23
	v_exp_f32_e32 v25, v23
	v_rcp_f32_e32 v23, v1
	v_add_f32_e32 v1, 1.0, v5
	v_rcp_f32_e32 v24, v1
	v_add_f32_e32 v1, 1.0, v25
	s_nop 0
	v_pk_mul_f32 v[18:19], v[28:29], v[18:19]
	v_rcp_f32_e32 v25, v1
	v_pk_mul_f32 v[18:19], v[22:23], v[18:19]
	v_pk_mul_f32 v[16:17], v[16:17], v[4:5] op_sel_hi:[1,0]
	v_and_b32_sdwa v5, v18, v247 dst_sel:DWORD dst_unused:UNUSED_PAD src0_sel:WORD_1 src1_sel:DWORD
	v_pk_mul_f32 v[16:17], v[30:31], v[16:17]
	v_and_b32_sdwa v1, v19, v247 dst_sel:DWORD dst_unused:UNUSED_PAD src0_sel:WORD_1 src1_sel:DWORD
	v_add3_u32 v5, v18, v5, s73
	v_pk_mul_f32 v[16:17], v[24:25], v[16:17]
	v_add3_u32 v1, v19, v1, s73
	v_lshrrev_b32_e32 v5, 16, v5
	v_and_or_b32 v22, v1, s33, v5
	v_and_b32_sdwa v5, v16, v247 dst_sel:DWORD dst_unused:UNUSED_PAD src0_sel:WORD_1 src1_sel:DWORD
	v_and_b32_sdwa v1, v17, v247 dst_sel:DWORD dst_unused:UNUSED_PAD src0_sel:WORD_1 src1_sel:DWORD
	v_add3_u32 v5, v16, v5, s73
	v_add3_u32 v1, v17, v1, s73
	v_lshrrev_b32_e32 v5, 16, v5
	v_and_or_b32 v23, v1, s33, v5
	v_permlane32_swap_b32_e32 v20, v22
	s_nop 0
	v_permlane32_swap_b32_e32 v21, v23
	global_store_dwordx4 v[10:11], v[20:23], off offset:160
	s_nop 1
	v_mov_b64_e32 v[24:25], v[204:205]
	s_nop 1
	v_mov_b64_e32 v[16:17], v[206:207]
	v_mov_b64_e32 v[18:19], v[208:209]
	s_nop 1
	v_mov_b64_e32 v[26:27], v[210:211]
	s_nop 0
	s_nop 1
	v_mov_b64_e32 v[20:21], v[212:213]
	v_mov_b64_e32 v[22:23], v[214:215]
	s_nop 0
	v_lshlrev_b32_e32 v1, 16, v24
	v_mul_f32_e32 v1, 0xbfb8aa3b, v1
	v_and_b32_e32 v5, 0xffff0000, v24
	v_exp_f32_e32 v1, v1
	v_mul_f32_e32 v5, 0xbfb8aa3b, v5
	v_exp_f32_e32 v5, v5
	v_add_f32_e32 v1, 1.0, v1
	v_rcp_f32_e32 v24, v1
	v_pk_mul_f32 v[14:15], v[14:15], v[4:5] op_sel_hi:[1,0]
	v_add_f32_e32 v1, 1.0, v5
	v_lshlrev_b32_e32 v5, 16, v25
	s_nop 0
	v_pk_mul_f32 v[14:15], v[16:17], v[14:15]
	v_mul_f32_e32 v5, 0xbfb8aa3b, v5
	v_and_b32_e32 v16, 0xffff0000, v25
	v_exp_f32_e32 v5, v5
	v_mul_f32_e32 v16, 0xbfb8aa3b, v16
	v_exp_f32_e32 v17, v16
	v_rcp_f32_e32 v25, v1
	v_add_f32_e32 v1, 1.0, v5
	v_rcp_f32_e32 v16, v1
	v_add_f32_e32 v1, 1.0, v17
	v_rcp_f32_e32 v17, v1
	v_pk_mul_f32 v[14:15], v[24:25], v[14:15]
	v_pk_mul_f32 v[12:13], v[12:13], v[4:5] op_sel_hi:[1,0]
	v_and_b32_sdwa v5, v14, v247 dst_sel:DWORD dst_unused:UNUSED_PAD src0_sel:WORD_1 src1_sel:DWORD
	v_pk_mul_f32 v[12:13], v[18:19], v[12:13]
	v_and_b32_sdwa v1, v15, v247 dst_sel:DWORD dst_unused:UNUSED_PAD src0_sel:WORD_1 src1_sel:DWORD
	v_add3_u32 v5, v14, v5, s73
	v_pk_mul_f32 v[16:17], v[16:17], v[12:13]
	v_add3_u32 v1, v15, v1, s73
	v_lshrrev_b32_e32 v5, 16, v5
	v_and_or_b32 v12, v1, s33, v5
	v_and_b32_sdwa v5, v16, v247 dst_sel:DWORD dst_unused:UNUSED_PAD src0_sel:WORD_1 src1_sel:DWORD
	v_and_b32_sdwa v1, v17, v247 dst_sel:DWORD dst_unused:UNUSED_PAD src0_sel:WORD_1 src1_sel:DWORD
	s_nop 0
	v_lshlrev_b32_e32 v13, 16, v26
	v_add3_u32 v5, v16, v5, s73
	v_add3_u32 v1, v17, v1, s73
	v_mul_f32_e32 v13, 0xbfb8aa3b, v13
	v_lshrrev_b32_e32 v5, 16, v5
	v_exp_f32_e32 v14, v13
	v_and_or_b32 v13, v1, s33, v5
	v_and_b32_e32 v5, 0xffff0000, v26
	v_mul_f32_e32 v5, 0xbfb8aa3b, v5
	v_exp_f32_e32 v5, v5
	v_add_f32_e32 v1, 1.0, v14
	v_rcp_f32_e32 v14, v1
	v_and_b32_e32 v15, 0xffff0000, v27
	v_pk_mul_f32 v[8:9], v[8:9], v[4:5] op_sel_hi:[1,0]
	v_add_f32_e32 v1, 1.0, v5
	v_lshlrev_b32_e32 v5, 16, v27
	v_mul_f32_e32 v5, 0xbfb8aa3b, v5
	v_exp_f32_e32 v5, v5
	v_mul_f32_e32 v15, 0xbfb8aa3b, v15
	v_exp_f32_e32 v17, v15
	v_rcp_f32_e32 v15, v1
	v_add_f32_e32 v1, 1.0, v5
	v_rcp_f32_e32 v16, v1
	v_add_f32_e32 v1, 1.0, v17
	s_nop 0
	v_pk_mul_f32 v[8:9], v[20:21], v[8:9]
	v_rcp_f32_e32 v17, v1
	v_pk_mul_f32 v[8:9], v[14:15], v[8:9]
	v_pk_mul_f32 v[6:7], v[6:7], v[4:5] op_sel_hi:[1,0]
	v_and_b32_sdwa v5, v8, v247 dst_sel:DWORD dst_unused:UNUSED_PAD src0_sel:WORD_1 src1_sel:DWORD
	v_pk_mul_f32 v[6:7], v[22:23], v[6:7]
	v_and_b32_sdwa v1, v9, v247 dst_sel:DWORD dst_unused:UNUSED_PAD src0_sel:WORD_1 src1_sel:DWORD
	v_add3_u32 v5, v8, v5, s73
	v_pk_mul_f32 v[6:7], v[16:17], v[6:7]
	v_add3_u32 v1, v9, v1, s73
	v_lshrrev_b32_e32 v5, 16, v5
	v_and_or_b32 v14, v1, s33, v5
	v_and_b32_sdwa v5, v6, v247 dst_sel:DWORD dst_unused:UNUSED_PAD src0_sel:WORD_1 src1_sel:DWORD
	v_and_b32_sdwa v1, v7, v247 dst_sel:DWORD dst_unused:UNUSED_PAD src0_sel:WORD_1 src1_sel:DWORD
	v_add3_u32 v5, v6, v5, s73
	v_add3_u32 v1, v7, v1, s73
	v_lshrrev_b32_e32 v5, 16, v5
	v_and_or_b32 v15, v1, s33, v5
	v_permlane32_swap_b32_e32 v12, v14
	s_nop 0
	v_permlane32_swap_b32_e32 v13, v15
	global_store_dwordx4 v[10:11], v[12:15], off offset:192
	s_nop 1
	v_mov_b64_e32 v[16:17], v[216:217]
	s_nop 1
	v_mov_b64_e32 v[6:7], v[218:219]
	v_mov_b64_e32 v[8:9], v[220:221]
	s_nop 1
	v_mov_b64_e32 v[18:19], v[222:223]
	s_nop 0
	s_nop 1
	v_mov_b64_e32 v[12:13], v[236:237]
	v_mov_b64_e32 v[14:15], v[238:239]
	s_nop 0
	v_lshlrev_b32_e32 v1, 16, v16
	v_and_b32_e32 v5, 0xffff0000, v16
	v_mul_f32_e32 v1, 0xbfb8aa3b, v1
	v_mul_f32_e32 v5, 0xbfb8aa3b, v5
	v_exp_f32_e32 v1, v1
	v_exp_f32_e32 v5, v5
	v_add_f32_e32 v1, 1.0, v1
	v_pk_mul_f32 v[2:3], v[2:3], v[4:5] op_sel_hi:[1,0]
	v_add_f32_e32 v5, 1.0, v5
	s_nop 0
	v_pk_mul_f32 v[2:3], v[6:7], v[2:3]
	v_rcp_f32_e32 v6, v1
	v_lshlrev_b32_e32 v1, 16, v17
	v_rcp_f32_e32 v7, v5
	v_mul_f32_e32 v1, 0xbfb8aa3b, v1
	v_and_b32_e32 v5, 0xffff0000, v17
	v_exp_f32_e32 v1, v1
	v_mul_f32_e32 v5, 0xbfb8aa3b, v5
	v_exp_f32_e32 v5, v5
	v_pk_mul_f32 v[2:3], v[6:7], v[2:3]
	v_add_f32_e32 v1, 1.0, v1
	v_rcp_f32_e32 v16, v1
	v_add_f32_e32 v1, 1.0, v5
	v_and_b32_sdwa v5, v2, v247 dst_sel:DWORD dst_unused:UNUSED_PAD src0_sel:WORD_1 src1_sel:DWORD
	v_rcp_f32_e32 v17, v1
	v_and_b32_sdwa v1, v3, v247 dst_sel:DWORD dst_unused:UNUSED_PAD src0_sel:WORD_1 src1_sel:DWORD
	v_add3_u32 v2, v2, v5, s73
	v_add3_u32 v1, v3, v1, s73
	v_lshrrev_b32_e32 v2, 16, v2
	v_and_or_b32 v6, v1, s33, v2
	v_pk_mul_f32 v[2:3], v[72:73], v[4:5] op_sel_hi:[1,0]
	s_nop 0
	v_pk_mul_f32 v[2:3], v[8:9], v[2:3]
	s_nop 0
	v_pk_mul_f32 v[2:3], v[16:17], v[2:3]
	s_nop 0
	v_and_b32_sdwa v1, v3, v247 dst_sel:DWORD dst_unused:UNUSED_PAD src0_sel:WORD_1 src1_sel:DWORD
	v_add3_u32 v1, v3, v1, s73
	s_nop 0
	v_lshlrev_b32_e32 v3, 16, v18
	v_and_b32_sdwa v5, v2, v247 dst_sel:DWORD dst_unused:UNUSED_PAD src0_sel:WORD_1 src1_sel:DWORD
	v_mul_f32_e32 v3, 0xbfb8aa3b, v3
	v_add3_u32 v2, v2, v5, s73
	v_exp_f32_e32 v3, v3
	v_and_b32_e32 v5, 0xffff0000, v18
	v_mul_f32_e32 v5, 0xbfb8aa3b, v5
	v_exp_f32_e32 v5, v5
	v_lshrrev_b32_e32 v2, 16, v2
	v_and_or_b32 v7, v1, s33, v2
	v_add_f32_e32 v1, 1.0, v3
	v_lshlrev_b32_e32 v3, 16, v19
	v_mul_f32_e32 v3, 0xbfb8aa3b, v3
	v_rcp_f32_e32 v2, v1
	v_add_f32_e32 v1, 1.0, v5
	v_exp_f32_e32 v5, v3
	v_and_b32_e32 v3, 0xffff0000, v19
	v_mul_f32_e32 v3, 0xbfb8aa3b, v3
	v_exp_f32_e32 v8, v3
	v_rcp_f32_e32 v3, v1
	v_add_f32_e32 v1, 1.0, v5
	v_rcp_f32_e32 v16, v1
	v_add_f32_e32 v1, 1.0, v8
	v_pk_mul_f32 v[8:9], v[70:71], v[4:5] op_sel_hi:[1,0]
	v_rcp_f32_e32 v17, v1
	s_nop 0
	v_pk_mul_f32 v[8:9], v[12:13], v[8:9]
	s_nop 0
	v_pk_mul_f32 v[2:3], v[2:3], v[8:9]
	s_nop 0
	v_and_b32_sdwa v5, v2, v247 dst_sel:DWORD dst_unused:UNUSED_PAD src0_sel:WORD_1 src1_sel:DWORD
	v_and_b32_sdwa v1, v3, v247 dst_sel:DWORD dst_unused:UNUSED_PAD src0_sel:WORD_1 src1_sel:DWORD
	v_add3_u32 v2, v2, v5, s73
	v_add3_u32 v1, v3, v1, s73
	v_lshrrev_b32_e32 v2, 16, v2
	v_and_or_b32 v8, v1, s33, v2
	v_pk_mul_f32 v[2:3], v[68:69], v[4:5] op_sel_hi:[1,0]
	s_nop 0
	v_permlane32_swap_b32_e32 v6, v8
	v_pk_mul_f32 v[2:3], v[14:15], v[2:3]
	s_nop 0
	v_pk_mul_f32 v[2:3], v[16:17], v[2:3]
	s_nop 0
	v_and_b32_sdwa v4, v2, v247 dst_sel:DWORD dst_unused:UNUSED_PAD src0_sel:WORD_1 src1_sel:DWORD
	v_and_b32_sdwa v1, v3, v247 dst_sel:DWORD dst_unused:UNUSED_PAD src0_sel:WORD_1 src1_sel:DWORD
	v_add3_u32 v2, v2, v4, s73
	v_add3_u32 v1, v3, v1, s73
	v_lshrrev_b32_e32 v2, 16, v2
	v_and_or_b32 v9, v1, s33, v2
	s_nop 1
	v_permlane32_swap_b32_e32 v7, v9
	global_store_dwordx4 v[10:11], v[6:9], off offset:224
	s_barrier
	s_branch .LBB0_619
